# speedup vs baseline: 1.0192x; 1.0137x over previous
; __device__ __forceinline__ void sample_merge_all(const Params& p, char* lds) {
;     unsigned char* ws = PWS; const bf16_t* proj = (const bf16_t*)(ws + WS_PROJ); const bf16_t* ps = proj + (size_t)TP * NP; bf16_t* H = (bf16_t*)(ws + WS_H) + (size_t)TP * 2048;
;     float* red = (float*)lds;
;     for (int it = blockIdx.x; it < 256; it += gridDim.x) {
;         const int rb = it >> 6, cb = it & 63; float a0, a1, b0, b1, c0, c1;
; __global__ void __launch_bounds__(NTH, 2) mega(Params p) {
;     ...
;     for (int ph = p.ph_lo; ph < p.ph_hi; ++ph) {
;         const int l = ph / 7, s0 = ph - 7 * l, s = s0 < 4 ? s0 : (s0 == 4 ? 5 : (s0 == 5 ? 6 : 8));
.LBB0_9:
	s_xor_b64 s[4:5], s[6:7], -1
	v_writelane_b32 v246, s4, 33
	s_nop 1
	v_writelane_b32 v246, s5, 34
	s_mul_hi_i32 s4, s56, 0x92492493
	s_add_i32 s4, s4, s56
	s_lshr_b32 s5, s4, 31
	s_ashr_i32 s4, s4, 2
	s_add_i32 s6, s4, s5
	s_mov_b32 s4, s6
	v_writelane_b32 v246, s4, 35
	s_nop 1
	v_writelane_b32 v246, s5, 36
	s_mul_i32 s4, s6, -7
	s_add_i32 s4, s4, s56
	s_cmp_eq_u32 s4, 5
	s_cselect_b32 s5, 6, 8
	s_cmp_lg_u32 s4, 4
	s_cselect_b32 s5, s5, 5
	s_cmp_lt_i32 s4, 4
	s_cselect_b32 s4, s4, s5
	v_writelane_b32 v246, s4, 37
	s_cmp_lt_i32 s4, 3
	s_mov_b64 s[4:5], 0
	s_mov_b64 s[6:7], -1
	v_writelane_b32 v246, s4, 38
	s_nop 1
	v_writelane_b32 v246, s5, 39
	s_cbranch_scc1 .LBB0_191
	v_readlane_b32 s4, v246, 37
	s_cmp_gt_i32 s4, 4
	s_cbranch_scc0 .LBB0_49
	s_cmp_gt_i32 s4, 5
	v_writelane_b32 v246, s56, 40
	s_nop 1
	v_writelane_b32 v246, s57, 41
	s_cbranch_scc0 .LBB0_50
	s_cmp_eq_u32 s4, 6
	s_mov_b64 s[4:5], -1
	s_mov_b32 s88, 0x331d9000
	s_cbranch_scc0 .LBB0_58
	v_readlane_b32 s4, v247, 61
	s_nop 3
	s_bitcmp1_b32 s4, 0
	s_cbranch_scc0 .Lsm_skipfirst
	v_readlane_b32 s4, v249, 8
	v_readlane_b32 s5, v249, 9
	s_mov_b32 s6, 24
	s_andn2_b64 vcc, exec, s[4:5]
	s_movk_i32 s27, 0x1000
	s_cbranch_vccnz .Lsm_done
	s_ashr_i32 s7, s6, 31
	s_lshl_b64 s[4:5], s[6:7], 3
	s_add_u32 s4, s0, s4
	s_addc_u32 s5, s1, s5
	s_load_dwordx2 s[6:7], s[4:5], 0x0
	v_readlane_b32 s4, v247, 61
	v_readlane_b32 s5, v247, 62
	s_waitcnt lgkmcnt(0)
	s_add_u32 s8, s6, 0x3b2c1000
	s_addc_u32 s9, s7, 0
	s_add_u32 s10, s6, 0x80a1000
	s_addc_u32 s11, s7, 0
	s_add_u32 s12, s6, 0x4800000
	s_addc_u32 s13, s7, 0
	s_add_u32 s14, s6, 0x2a9a3080
	s_addc_u32 s15, s7, 0
	s_add_u32 s16, s6, 0x4c00000
	s_addc_u32 s17, s7, 0
	s_add_u32 s18, s6, 0xa121000
	s_addc_u32 s19, s7, 0
	s_add_u32 s20, s6, 0x5400000
	s_addc_u32 s21, s7, 0

; __device__ __forceinline__ int opaque_tid() { int t = threadIdx.x; asm volatile("" : "+v"(t)); return t; }
; #define G_STA(bufoff, gbase, ld) G_STAGE(bufoff, gbase, RA0, RA1, ld)
; #define G_STB(bufoff, gbase, ld) G_STAGE(bufoff, gbase, RB0, RB1, ld)
; #define G_WAIT_V(n) asm volatile("s_waitcnt vmcnt(" #n ")" ::: "memory")
; #define G_BAR __builtin_amdgcn_s_barrier()
; template <bool PERM, class SchedT, class Epi>
; __device__ __forceinline__ void gemm_phase(LAS unsigned char* lds, const SchedT& S, const Epi& E) {
;     const int tid = opaque_tid(), wid = __builtin_amdgcn_readfirstlane(tid >> 6), lane = tid & 63, wr = wid >> 2, wc = wid & 3, fr = lane & 15, fq = lane >> 4;
;     int R0, C0, R1, C1; stage_rc(tid * 16, R0, C0); stage_rc(tid * 16 + 8192, R1, C1);
;     const unsigned RA0 = (unsigned)R0 * 2u, RA1 = (unsigned)R1 * 2u, RB0 = (unsigned)(PERM ? ((R0 & ~31) + perm32(R0 & 31)) : R0) * 2u, RB1 = (unsigned)(PERM ? ((R1 & ~31) + perm32(R1 & 31)) : R1) * 2u;
;     const unsigned CC0 = (unsigned)C0 * 2u, CC1 = (unsigned)C1 * 2u;
;     const size_t kstep = (size_t)(BK * 2);
;     const unsigned ldsw = (unsigned)wid * 1024u;
;     const int aoff = lds_byte(wr * 64 + fr, fq * 8), boff = lds_byte(wc * 32 + fr, fq * 8);
;     ...
;     UnitD cur, nxt; int ui = 0;
;     if (!S.get(0, cur)) return;
;     f32x4 acc[2][2][4][2];
; #pragma unroll
;     for (int a = 0; a < 2; ++a)
; #pragma unroll
;         for (int b = 0; b < 2; ++b)
; #pragma unroll
;             for (int m = 0; m < 4; ++m)
; #pragma unroll
;                 for (int n = 0; n < 2; ++n) acc[a][b][m][n] = (f32x4){0.f, 0.f, 0.f, 0.f};
;     bf16x8 At[4][2], B0[2][2], B1[2][2];
;     const char* cA = cur.A; const char* cB = cur.B;
;     int lda = cur.lda, K = cur.K;
;     ...
;     G_STB(G_SB(0, 0), cB, K); G_STA(G_SA(0, 0), cA, lda); G_STB(G_SB(0, 1), cB + HSTEP(K), K); G_STA(G_SA(0, 1), cA + HSTEP(lda), lda);
;     if (wr == 1) G_BAR;
;     G_WAIT_V(4); G_BAR;
;     G_STB(G_SB(1, 0), cB + kstep, K); G_STA(G_SA(1, 0), cA + kstep, lda); G_STB(G_SB(1, 1), cB + HSTEP(K) + kstep, K);
;     G_WAIT_V(6); G_BAR;
.Lsm_done:
	s_waitcnt vmcnt(0) lgkmcnt(0)
	s_barrier
.Lsm_skipfirst:
	v_mov_b32_e32 v12, v159
	s_andn2_b64 vcc, exec, s[64:65]
	v_readfirstlane_b32 s4, v12
	s_cbranch_vccnz .LBB0_54
	v_ashrrev_i32_e32 v2, 31, v12
	v_lshrrev_b32_e32 v2, 26, v2
	v_add_u32_e32 v2, v12, v2
	v_ashrrev_i32_e32 v8, 6, v2
	v_bfe_i32 v2, v12, 27, 1
	v_lshlrev_b32_e32 v0, 4, v12
	v_lshrrev_b32_e32 v2, 22, v2
	v_add_u32_e32 v2, v0, v2
	v_and_b32_e32 v2, 0xfffffc00, v2
	v_sub_u32_e32 v2, v0, v2
	v_lshrrev_b32_e32 v3, 4, v2
	v_bitop3_b32 v3, v3, v2, 32 bitop3:0x6c
	v_ashrrev_i32_e32 v2, 31, v2
	v_lshrrev_b32_e32 v2, 26, v2
	v_add_u32_e32 v2, v3, v2
	v_ashrrev_i32_e32 v2, 6, v2
	v_mul_i32_i24_e32 v6, 64, v2
	v_sub_u32_e32 v3, v3, v6
	v_ashrrev_i16_sdwa v3, v184, sext(v3) dst_sel:DWORD dst_unused:UNUSED_PAD src0_sel:DWORD src1_sel:BYTE_0
	v_add_u32_e32 v0, 0x2000, v0
	v_bfe_i32 v9, v3, 0, 16
	v_ashrrev_i32_e32 v3, 31, v0
	v_lshrrev_b32_e32 v3, 22, v3
	v_add_u32_e32 v3, v0, v3
	v_ashrrev_i32_e32 v10, 10, v3
	v_mul_i32_i24_e32 v3, 0x400, v10
	v_sub_u32_e32 v0, v0, v3
	v_lshrrev_b32_e32 v3, 4, v0
	v_bitop3_b32 v0, v3, v0, 32 bitop3:0x6c
	v_ashrrev_i32_e32 v6, 31, v0
	v_lshrrev_b32_e32 v6, 26, v6
	v_lshlrev_b32_e32 v4, 3, v8
	v_add_u32_e32 v6, v0, v6
	v_and_b32_e32 v4, -16, v4
	v_ashrrev_i32_e32 v7, 6, v6
	v_and_b32_e32 v6, 0xc0, v6
	v_add_u32_e32 v4, v2, v4
	v_sub_u32_e32 v0, v0, v6
	v_lshlrev_b32_e32 v3, 3, v10
	v_lshlrev_b32_e32 v11, 5, v10
	v_ashrrev_i16_sdwa v0, v184, sext(v0) dst_sel:DWORD dst_unused:UNUSED_PAD src0_sel:DWORD src1_sel:BYTE_0
	v_lshlrev_b32_e32 v139, 1, v4
	v_lshrrev_b32_e32 v6, 2, v4
	v_and_b32_e32 v2, 3, v2
	s_mov_b32 s5, 0x7fffffe0
	v_and_b32_e32 v3, -16, v3
	v_and_b32_e32 v15, 32, v11
	v_bfe_i32 v11, v0, 0, 16
	v_and_b32_e32 v0, 24, v139
	v_and_b32_e32 v6, 4, v6
	v_and_or_b32 v2, v4, s5, v2
	s_ashr_i32 s6, s4, 6
	v_lshlrev_b32_e32 v5, 5, v8
	v_add_u32_e32 v3, v7, v3
	v_or3_b32 v13, v2, v6, v0
	v_and_b32_e32 v6, 3, v7
	v_and_b32_e32 v5, 32, v5
	v_lshlrev_b32_e32 v141, 1, v3
	v_lshrrev_b32_e32 v2, 2, v3
	v_and_or_b32 v6, v3, s5, v6
	s_lshl_b32 s5, s6, 10
	v_and_b32_e32 v0, 24, v141
	v_and_b32_e32 v2, 4, v2
	v_add_lshl_u32 v138, v5, v9, 1
	s_add_i32 s30, s5, 0
	v_readlane_b32 s8, v248, 18
	v_or3_b32 v14, v6, v2, v0
	v_add_lshl_u32 v140, v15, v11, 1
	v_lshl_add_u32 v0, v13, 12, v138
	s_add_i32 m0, s30, 0x10000
	v_readlane_b32 s9, v248, 19
	v_lshl_add_u32 v2, v14, 12, v140
	v_readlane_b32 s10, v248, 22
	v_readlane_b32 s11, v248, 23
	s_add_i32 s31, s30, 0x2000
	s_add_i32 s34, s30, 0x4000
	global_load_lds_dwordx4 v0, s[8:9]
	s_add_i32 m0, s30, 0x12000
	s_add_i32 s35, s30, 0x6000
	global_load_lds_dwordx4 v2, s[8:9]
	v_mad_u64_u32 v[4:5], s[8:9], v4, s3, v[138:139]
	s_mov_b32 m0, s30
	v_mad_u64_u32 v[6:7], s[8:9], v3, s3, v[140:141]
	global_load_lds_dwordx4 v4, s[10:11]
	s_mov_b32 m0, s31
	v_readlane_b32 s8, v248, 20
	global_load_lds_dwordx4 v6, s[10:11]
	s_add_i32 m0, s30, 0x14000
	v_readlane_b32 s9, v248, 21
	s_ashr_i32 s7, s4, 8
	v_readlane_b32 s51, v248, 14
	v_readlane_b32 s52, v248, 15
	v_readlane_b32 s53, v249, 6
	v_readlane_b32 s64, v249, 7
	global_load_lds_dwordx4 v0, s[8:9]
	s_add_i32 m0, s30, 0x16000
	s_cmp_lg_u32 s7, 1
	global_load_lds_dwordx4 v2, s[8:9]
	v_readlane_b32 s8, v248, 24
	s_mov_b32 m0, s34
	v_readlane_b32 s9, v248, 25
	s_movk_i32 s65, 0x6000
	s_movk_i32 s70, 0x5000
	s_mov_b64 s[76:77], 0x5080
	s_nop 1
	global_load_lds_dwordx4 v4, s[8:9]
	s_mov_b32 m0, s35
	s_nop 0
	global_load_lds_dwordx4 v6, s[8:9]
	s_cbranch_scc1 .LBB0_16
	s_barrier

; __global__ void __launch_bounds__(NTH, 2) mega(Params p) {
;     ...
;             gemm_phase<true>(lds, S, EpiMerge3{proj, (const bf16_t*)(ws + WS_PA), (const bf16_t*)(ws + WS_PB), (bf16_t*)(ws + WS_H)});
;             sample_merge_all(p, (char*)lds_raw);
.LBB0_54:
	v_readlane_b32 s4, v247, 61
	s_nop 3
	s_bitcmp1_b32 s4, 0
	s_cbranch_scc0 .Lsm_orig
	s_movk_i32 s27, 0x1000
	s_branch .LBB0_57
